# v103 + back-edge rotation (asm guide 7.11): loop-control SALU moved ahead of the loop-back barrier in the 9 GEMM K-loops and the attention loop
# baseline (speedup 1.0000x reference)
.LBB0_270:
	s_waitcnt lgkmcnt(0)
	s_barrier
	s_setprio 1
	s_waitcnt lgkmcnt(0)
	v_mfma_f32_16x16x32_bf16 v[58:61], v[146:149], v[186:189], v[58:61]
	v_mfma_f32_16x16x32_bf16 v[50:53], v[154:157], v[186:189], v[50:53]
	v_mfma_f32_16x16x32_bf16 v[42:45], v[146:149], v[178:181], v[42:45]
	v_mfma_f32_16x16x32_bf16 v[34:37], v[154:157], v[178:181], v[34:37]
	v_mfma_f32_16x16x32_bf16 v[26:29], v[146:149], v[170:173], v[26:29]
	v_mfma_f32_16x16x32_bf16 v[18:21], v[154:157], v[170:173], v[18:21]
	v_mfma_f32_16x16x32_bf16 v[10:13], v[146:149], v[162:165], v[10:13]
	v_mfma_f32_16x16x32_bf16 v[2:5], v[154:157], v[162:165], v[2:5]
	v_mfma_f32_16x16x32_bf16 v[58:61], v[150:153], v[190:193], v[58:61]
	v_mfma_f32_16x16x32_bf16 v[50:53], v[158:161], v[190:193], v[50:53]
	v_mfma_f32_16x16x32_bf16 v[42:45], v[150:153], v[182:185], v[42:45]
	v_mfma_f32_16x16x32_bf16 v[34:37], v[158:161], v[182:185], v[34:37]
	v_mfma_f32_16x16x32_bf16 v[26:29], v[150:153], v[174:177], v[26:29]
	v_mfma_f32_16x16x32_bf16 v[18:21], v[158:161], v[174:177], v[18:21]
	v_mfma_f32_16x16x32_bf16 v[10:13], v[150:153], v[166:169], v[10:13]
	v_mfma_f32_16x16x32_bf16 v[2:5], v[158:161], v[166:169], v[2:5]
	s_setprio 0
	s_setprio 1
	v_mfma_f32_16x16x32_bf16 v[62:65], v[130:133], v[186:189], v[62:65]
	v_mfma_f32_16x16x32_bf16 v[54:57], v[138:141], v[186:189], v[54:57]
	v_mfma_f32_16x16x32_bf16 v[46:49], v[130:133], v[178:181], v[46:49]
	v_mfma_f32_16x16x32_bf16 v[38:41], v[138:141], v[178:181], v[38:41]
	v_mfma_f32_16x16x32_bf16 v[30:33], v[130:133], v[170:173], v[30:33]
	v_mfma_f32_16x16x32_bf16 v[22:25], v[138:141], v[170:173], v[22:25]
	v_mfma_f32_16x16x32_bf16 v[14:17], v[130:133], v[162:165], v[14:17]
	v_mfma_f32_16x16x32_bf16 v[6:9], v[138:141], v[162:165], v[6:9]
	v_mfma_f32_16x16x32_bf16 v[62:65], v[134:137], v[190:193], v[62:65]
	v_mfma_f32_16x16x32_bf16 v[54:57], v[142:145], v[190:193], v[54:57]
	v_mfma_f32_16x16x32_bf16 v[46:49], v[134:137], v[182:185], v[46:49]
	v_mfma_f32_16x16x32_bf16 v[38:41], v[142:145], v[182:185], v[38:41]
	v_mfma_f32_16x16x32_bf16 v[30:33], v[134:137], v[174:177], v[30:33]
	v_mfma_f32_16x16x32_bf16 v[22:25], v[142:145], v[174:177], v[22:25]
	v_mfma_f32_16x16x32_bf16 v[14:17], v[134:137], v[166:169], v[14:17]
	v_mfma_f32_16x16x32_bf16 v[6:9], v[142:145], v[166:169], v[6:9]
	s_setprio 0
	s_add_i32 s33, s33, 2
	s_add_u32 s42, s42, 0x100
	s_addc_u32 s43, s43, 0
	s_cmp_gt_u32 s33, 13
	s_barrier
	s_cbranch_scc1 .LBB0_283

.LBB0_381:
	s_waitcnt lgkmcnt(0)
	s_barrier
	s_setprio 1
	s_waitcnt lgkmcnt(0)
	v_mfma_f32_16x16x32_bf16 v[6:9], v[158:161], v[186:189], v[6:9]
	v_mfma_f32_16x16x32_bf16 v[10:13], v[166:169], v[186:189], v[10:13]
	v_mfma_f32_16x16x32_bf16 v[14:17], v[158:161], v[178:181], v[14:17]
	v_mfma_f32_16x16x32_bf16 v[18:21], v[166:169], v[178:181], v[18:21]
	v_mfma_f32_16x16x32_bf16 v[22:25], v[158:161], v[130:133], v[22:25]
	v_mfma_f32_16x16x32_bf16 v[26:29], v[166:169], v[130:133], v[26:29]
	v_mfma_f32_16x16x32_bf16 v[30:33], v[158:161], v[98:101], v[30:33]
	v_mfma_f32_16x16x32_bf16 v[34:37], v[166:169], v[98:101], v[34:37]
	v_mfma_f32_16x16x32_bf16 v[6:9], v[162:165], v[190:193], v[6:9]
	v_mfma_f32_16x16x32_bf16 v[10:13], v[170:173], v[190:193], v[10:13]
	v_mfma_f32_16x16x32_bf16 v[14:17], v[162:165], v[182:185], v[14:17]
	v_mfma_f32_16x16x32_bf16 v[18:21], v[170:173], v[182:185], v[18:21]
	v_mfma_f32_16x16x32_bf16 v[22:25], v[162:165], v[174:177], v[22:25]
	v_mfma_f32_16x16x32_bf16 v[26:29], v[170:173], v[174:177], v[26:29]
	v_mfma_f32_16x16x32_bf16 v[30:33], v[162:165], v[102:105], v[30:33]
	v_mfma_f32_16x16x32_bf16 v[34:37], v[170:173], v[102:105], v[34:37]
	s_setprio 0
	s_setprio 1
	v_mfma_f32_16x16x32_bf16 v[38:41], v[142:145], v[186:189], v[38:41]
	v_mfma_f32_16x16x32_bf16 v[42:45], v[150:153], v[186:189], v[42:45]
	v_mfma_f32_16x16x32_bf16 v[46:49], v[142:145], v[178:181], v[46:49]
	v_mfma_f32_16x16x32_bf16 v[50:53], v[150:153], v[178:181], v[50:53]
	v_mfma_f32_16x16x32_bf16 v[54:57], v[142:145], v[130:133], v[54:57]
	v_mfma_f32_16x16x32_bf16 v[62:65], v[150:153], v[130:133], v[62:65]
	v_mfma_f32_16x16x32_bf16 v[66:69], v[142:145], v[98:101], v[66:69]
	v_mfma_f32_16x16x32_bf16 v[70:73], v[150:153], v[98:101], v[70:73]
	v_mfma_f32_16x16x32_bf16 v[38:41], v[146:149], v[190:193], v[38:41]
	v_mfma_f32_16x16x32_bf16 v[42:45], v[154:157], v[190:193], v[42:45]
	v_mfma_f32_16x16x32_bf16 v[46:49], v[146:149], v[182:185], v[46:49]
	v_mfma_f32_16x16x32_bf16 v[50:53], v[154:157], v[182:185], v[50:53]
	v_mfma_f32_16x16x32_bf16 v[54:57], v[146:149], v[174:177], v[54:57]
	v_mfma_f32_16x16x32_bf16 v[62:65], v[154:157], v[174:177], v[62:65]
	v_mfma_f32_16x16x32_bf16 v[66:69], v[146:149], v[102:105], v[66:69]
	v_mfma_f32_16x16x32_bf16 v[70:73], v[154:157], v[102:105], v[70:73]
	s_setprio 0
	s_add_i32 s33, s33, 2
	s_add_u32 s42, s42, 0x100
	s_addc_u32 s43, s43, 0
	s_cmp_gt_u32 s33, 41
	s_barrier
	s_cbranch_scc1 .LBB0_394

.LBB0_460:
	s_waitcnt lgkmcnt(0)
	s_barrier
	s_setprio 1
	s_waitcnt lgkmcnt(0)
	v_mfma_f32_16x16x32_bf16 v[62:65], v[154:157], v[186:189], v[62:65]
	v_mfma_f32_16x16x32_bf16 v[54:57], v[146:149], v[186:189], v[54:57]
	v_mfma_f32_16x16x32_bf16 v[46:49], v[154:157], v[178:181], v[46:49]
	v_mfma_f32_16x16x32_bf16 v[38:41], v[146:149], v[178:181], v[38:41]
	v_mfma_f32_16x16x32_bf16 v[30:33], v[154:157], v[170:173], v[30:33]
	v_mfma_f32_16x16x32_bf16 v[22:25], v[146:149], v[170:173], v[22:25]
	v_mfma_f32_16x16x32_bf16 v[14:17], v[154:157], v[162:165], v[14:17]
	v_mfma_f32_16x16x32_bf16 v[6:9], v[146:149], v[162:165], v[6:9]
	v_mfma_f32_16x16x32_bf16 v[62:65], v[158:161], v[190:193], v[62:65]
	v_mfma_f32_16x16x32_bf16 v[54:57], v[150:153], v[190:193], v[54:57]
	v_mfma_f32_16x16x32_bf16 v[46:49], v[158:161], v[182:185], v[46:49]
	v_mfma_f32_16x16x32_bf16 v[38:41], v[150:153], v[182:185], v[38:41]
	v_mfma_f32_16x16x32_bf16 v[30:33], v[158:161], v[174:177], v[30:33]
	v_mfma_f32_16x16x32_bf16 v[22:25], v[150:153], v[174:177], v[22:25]
	v_mfma_f32_16x16x32_bf16 v[14:17], v[158:161], v[166:169], v[14:17]
	v_mfma_f32_16x16x32_bf16 v[6:9], v[150:153], v[166:169], v[6:9]
	s_setprio 0
	s_setprio 1
	v_mfma_f32_16x16x32_bf16 v[58:61], v[138:141], v[186:189], v[58:61]
	v_mfma_f32_16x16x32_bf16 v[50:53], v[130:133], v[186:189], v[50:53]
	v_mfma_f32_16x16x32_bf16 v[42:45], v[138:141], v[178:181], v[42:45]
	v_mfma_f32_16x16x32_bf16 v[34:37], v[130:133], v[178:181], v[34:37]
	v_mfma_f32_16x16x32_bf16 v[26:29], v[138:141], v[170:173], v[26:29]
	v_mfma_f32_16x16x32_bf16 v[18:21], v[130:133], v[170:173], v[18:21]
	v_mfma_f32_16x16x32_bf16 v[10:13], v[138:141], v[162:165], v[10:13]
	v_mfma_f32_16x16x32_bf16 v[2:5], v[130:133], v[162:165], v[2:5]
	v_mfma_f32_16x16x32_bf16 v[58:61], v[142:145], v[190:193], v[58:61]
	v_mfma_f32_16x16x32_bf16 v[50:53], v[134:137], v[190:193], v[50:53]
	v_mfma_f32_16x16x32_bf16 v[42:45], v[142:145], v[182:185], v[42:45]
	v_mfma_f32_16x16x32_bf16 v[34:37], v[134:137], v[182:185], v[34:37]
	v_mfma_f32_16x16x32_bf16 v[26:29], v[142:145], v[174:177], v[26:29]
	v_mfma_f32_16x16x32_bf16 v[18:21], v[134:137], v[174:177], v[18:21]
	v_mfma_f32_16x16x32_bf16 v[10:13], v[142:145], v[166:169], v[10:13]
	v_mfma_f32_16x16x32_bf16 v[2:5], v[134:137], v[166:169], v[2:5]
	s_setprio 0
	s_add_i32 s58, s58, 2
	s_add_u32 s44, s44, 0x100
	s_addc_u32 s45, s45, 0
	s_cmp_gt_u32 s58, 41
	s_barrier
	s_cbranch_scc1 .LBB0_473

.LBB0_790:
	s_waitcnt lgkmcnt(0)
	s_barrier
	s_setprio 1
	s_waitcnt lgkmcnt(0)
	v_mfma_f32_16x16x32_bf16 v[66:69], v[154:157], v[186:189], v[66:69]
	v_mfma_f32_16x16x32_bf16 v[62:65], v[146:149], v[186:189], v[62:65]
	v_mfma_f32_16x16x32_bf16 v[54:57], v[154:157], v[178:181], v[54:57]
	v_mfma_f32_16x16x32_bf16 v[50:53], v[146:149], v[178:181], v[50:53]
	v_mfma_f32_16x16x32_bf16 v[46:49], v[154:157], v[170:173], v[46:49]
	v_mfma_f32_16x16x32_bf16 v[42:45], v[146:149], v[170:173], v[42:45]
	v_mfma_f32_16x16x32_bf16 v[38:41], v[154:157], v[162:165], v[38:41]
	v_mfma_f32_16x16x32_bf16 v[34:37], v[146:149], v[162:165], v[34:37]
	v_mfma_f32_16x16x32_bf16 v[66:69], v[158:161], v[190:193], v[66:69]
	v_mfma_f32_16x16x32_bf16 v[62:65], v[150:153], v[190:193], v[62:65]
	v_mfma_f32_16x16x32_bf16 v[54:57], v[158:161], v[182:185], v[54:57]
	v_mfma_f32_16x16x32_bf16 v[50:53], v[150:153], v[182:185], v[50:53]
	v_mfma_f32_16x16x32_bf16 v[46:49], v[158:161], v[174:177], v[46:49]
	v_mfma_f32_16x16x32_bf16 v[42:45], v[150:153], v[174:177], v[42:45]
	v_mfma_f32_16x16x32_bf16 v[38:41], v[158:161], v[166:169], v[38:41]
	v_mfma_f32_16x16x32_bf16 v[34:37], v[150:153], v[166:169], v[34:37]
	s_setprio 0
	s_setprio 1
	v_mfma_f32_16x16x32_bf16 v[30:33], v[138:141], v[186:189], v[30:33]
	v_mfma_f32_16x16x32_bf16 v[26:29], v[130:133], v[186:189], v[26:29]
	v_mfma_f32_16x16x32_bf16 v[22:25], v[138:141], v[178:181], v[22:25]
	v_mfma_f32_16x16x32_bf16 v[18:21], v[130:133], v[178:181], v[18:21]
	v_mfma_f32_16x16x32_bf16 v[14:17], v[138:141], v[170:173], v[14:17]
	v_mfma_f32_16x16x32_bf16 v[10:13], v[130:133], v[170:173], v[10:13]
	v_mfma_f32_16x16x32_bf16 v[6:9], v[138:141], v[162:165], v[6:9]
	v_mfma_f32_16x16x32_bf16 v[2:5], v[130:133], v[162:165], v[2:5]
	v_mfma_f32_16x16x32_bf16 v[30:33], v[142:145], v[190:193], v[30:33]
	v_mfma_f32_16x16x32_bf16 v[26:29], v[134:137], v[190:193], v[26:29]
	v_mfma_f32_16x16x32_bf16 v[22:25], v[142:145], v[182:185], v[22:25]
	v_mfma_f32_16x16x32_bf16 v[18:21], v[134:137], v[182:185], v[18:21]
	v_mfma_f32_16x16x32_bf16 v[14:17], v[142:145], v[174:177], v[14:17]
	v_mfma_f32_16x16x32_bf16 v[10:13], v[134:137], v[174:177], v[10:13]
	v_mfma_f32_16x16x32_bf16 v[6:9], v[142:145], v[166:169], v[6:9]
	v_mfma_f32_16x16x32_bf16 v[2:5], v[134:137], v[166:169], v[2:5]
	s_setprio 0
	s_add_i32 s92, s92, 2
	s_add_u32 s80, s80, 0x100
	s_addc_u32 s81, s81, 0
	s_cmp_gt_u32 s92, 13
	s_barrier
	s_cbranch_scc1 .LBB0_803

.LBB0_1163:
	s_mov_b32 s24, s39
	s_mov_b32 s25, s38
	v_lshl_add_u64 v[118:119], v[146:147], 0, s[10:11]
	s_add_i32 s27, s33, s35
	s_mov_b32 m0, s27
	s_nop 0
	global_load_lds_dwordx4 v[118:119], off
	v_lshl_add_u64 v[118:119], v[148:149], 0, s[6:7]
	s_add_i32 s27, s39, s34
	s_mov_b32 m0, s27
	s_nop 0
	global_load_lds_dwordx4 v[118:119], off
	v_add_u32_e32 v156, s33, v3
	ds_read_b64_tr_b16 v[152:153], v156 offset:32768
	ds_read_b64_tr_b16 v[154:155], v156 offset:33280
	v_add_f32_e32 v118, v98, v99
	v_add_f32_e32 v118, v100, v118
	v_add_f32_e32 v118, v101, v118
	v_add_f32_e32 v118, v102, v118
	v_add_f32_e32 v118, v103, v118
	v_cvt_pk_bf16_f32 v178, v98, v99
	v_cvt_pk_bf16_f32 v179, v100, v101
	s_waitcnt lgkmcnt(9)
	v_mfma_f32_32x32x16_bf16 v[130:145], v[114:117], v[182:185], v[66:81]
	ds_read_b64_tr_b16 v[98:99], v156 offset:36864
	ds_read_b64_tr_b16 v[100:101], v156 offset:37376
	v_add_f32_e32 v114, v104, v118
	v_add_f32_e32 v114, v105, v114
	v_add_f32_e32 v114, v106, v114
	v_add_f32_e32 v157, v107, v114
	s_waitcnt lgkmcnt(10)
	v_mfma_f32_32x32x16_bf16 v[114:129], v[210:213], v[182:185], v[66:81]
	v_cvt_pk_bf16_f32 v180, v102, v103
	v_cvt_pk_bf16_f32 v181, v104, v105
	ds_read_b64_tr_b16 v[102:103], v156 offset:33792
	ds_read_b64_tr_b16 v[104:105], v156 offset:34304
	v_add_f32_e32 v157, v108, v157
	v_add_f32_e32 v157, v109, v157
	v_add_f32_e32 v157, v110, v157
	v_add_f32_e32 v157, v111, v157
	v_cvt_pk_bf16_f32 v170, v106, v107
	v_cvt_pk_bf16_f32 v171, v108, v109
	s_waitcnt lgkmcnt(11)
	v_mfma_f32_32x32x16_bf16 v[130:145], v[206:209], v[174:177], v[130:145]
	ds_read_b64_tr_b16 v[106:107], v156 offset:37888
	ds_read_b64_tr_b16 v[108:109], v156 offset:38400
	s_waitcnt lgkmcnt(12)
	v_mfma_f32_32x32x16_bf16 v[114:129], v[202:205], v[174:177], v[114:129]
	v_add_f32_e32 v157, v112, v157
	v_add_f32_e32 v157, v113, v157
	v_add_f32_e32 v157, v82, v157
	v_add_f32_e32 v157, v83, v157
	v_cvt_pk_bf16_f32 v172, v110, v111
	v_cvt_pk_bf16_f32 v173, v112, v113
	ds_read_b64_tr_b16 v[110:111], v156 offset:34816
	ds_read_b64_tr_b16 v[112:113], v156 offset:35328
	v_add_f32_e32 v157, v84, v157
	v_add_f32_e32 v157, v85, v157
	v_add_f32_e32 v157, v86, v157
	v_add_f32_e32 v157, v87, v157
	v_cvt_pk_bf16_f32 v166, v82, v83
	v_cvt_pk_bf16_f32 v167, v84, v85
	s_waitcnt lgkmcnt(13)
	v_mfma_f32_32x32x16_bf16 v[130:145], v[198:201], v[12:15], v[130:145]
	ds_read_b64_tr_b16 v[82:83], v156 offset:38912
	ds_read_b64_tr_b16 v[84:85], v156 offset:39424
	s_waitcnt lgkmcnt(14)
	v_mfma_f32_32x32x16_bf16 v[114:129], v[194:197], v[12:15], v[114:129]
	v_add_f32_e32 v157, v88, v157
	v_add_f32_e32 v157, v89, v157
	v_add_f32_e32 v157, v90, v157
	v_add_f32_e32 v157, v91, v157
	v_cvt_pk_bf16_f32 v168, v86, v87
	v_cvt_pk_bf16_f32 v169, v88, v89
	ds_read_b64_tr_b16 v[86:87], v156 offset:35840
	ds_read_b64_tr_b16 v[88:89], v156 offset:36352
	v_add_f32_e32 v157, v92, v157
	v_add_f32_e32 v157, v93, v157
	v_add_f32_e32 v157, v94, v157
	v_add_f32_e32 v157, v95, v157
	v_cvt_pk_bf16_f32 v162, v90, v91
	v_cvt_pk_bf16_f32 v163, v92, v93
	s_waitcnt lgkmcnt(14)
	v_mfma_f32_32x32x16_bf16 v[130:145], v[190:193], v[8:11], v[130:145]
	ds_read_b64_tr_b16 v[90:91], v156 offset:39936
	ds_read_b64_tr_b16 v[92:93], v156 offset:40448
	v_mfma_f32_32x32x16_bf16 v[114:129], v[186:189], v[8:11], v[114:129]
	v_add_f32_e32 v156, v96, v157
	v_add_f32_e32 v156, v97, v156
	v_cvt_pk_bf16_f32 v164, v94, v95
	v_cvt_pk_bf16_f32 v165, v96, v97
	v_add_f32_e32 v160, v219, v156
	s_waitcnt lgkmcnt(14)
	v_mfma_f32_32x32x16_bf16 v[34:49], v[178:181], v[152:155], v[34:49]
	v_exp_f32_e32 v130, v130
	v_exp_f32_e32 v131, v131
	v_exp_f32_e32 v132, v132
	v_exp_f32_e32 v133, v133
	s_waitcnt lgkmcnt(12)
	v_mfma_f32_32x32x16_bf16 v[50:65], v[178:181], v[98:101], v[50:65]
	v_exp_f32_e32 v134, v134
	v_exp_f32_e32 v135, v135
	v_exp_f32_e32 v136, v136
	v_exp_f32_e32 v137, v137
	v_add_u32_e32 v98, s24, v7
	ds_read_b128 v[94:97], v98
	ds_read_b128 v[152:155], v98 offset:512
	s_waitcnt lgkmcnt(12)
	v_mfma_f32_32x32x16_bf16 v[34:49], v[170:173], v[102:105], v[34:49]
	v_exp_f32_e32 v138, v138
	v_exp_f32_e32 v139, v139
	v_exp_f32_e32 v140, v140
	v_exp_f32_e32 v141, v141
	ds_read_b128 v[156:159], v98 offset:2048
	ds_read_b128 v[186:189], v98 offset:2560
	s_waitcnt lgkmcnt(12)
	v_mfma_f32_32x32x16_bf16 v[50:65], v[170:173], v[106:109], v[50:65]
	v_exp_f32_e32 v142, v142
	v_exp_f32_e32 v143, v143
	v_exp_f32_e32 v144, v144
	v_exp_f32_e32 v145, v145
	ds_read_b128 v[190:193], v98 offset:4096
	ds_read_b128 v[194:197], v98 offset:4608
	s_waitcnt lgkmcnt(12)
	v_mfma_f32_32x32x16_bf16 v[34:49], v[166:169], v[110:113], v[34:49]
	v_exp_f32_e32 v114, v114
	v_exp_f32_e32 v115, v115
	v_exp_f32_e32 v116, v116
	v_exp_f32_e32 v117, v117
	ds_read_b128 v[198:201], v98 offset:6144
	ds_read_b128 v[202:205], v98 offset:6656
	s_waitcnt lgkmcnt(12)
	v_mfma_f32_32x32x16_bf16 v[50:65], v[166:169], v[82:85], v[50:65]
	v_exp_f32_e32 v118, v118
	v_exp_f32_e32 v119, v119
	v_exp_f32_e32 v120, v120
	v_exp_f32_e32 v121, v121
	s_waitcnt lgkmcnt(10)
	v_mfma_f32_32x32x16_bf16 v[34:49], v[162:165], v[86:89], v[34:49]
	v_exp_f32_e32 v122, v122
	v_exp_f32_e32 v123, v123
	v_exp_f32_e32 v124, v124
	v_exp_f32_e32 v125, v125
	s_waitcnt lgkmcnt(8)
	v_mfma_f32_32x32x16_bf16 v[50:65], v[162:165], v[90:93], v[50:65]
	v_exp_f32_e32 v126, v126
	v_exp_f32_e32 v127, v127
	v_exp_f32_e32 v128, v128
	v_exp_f32_e32 v129, v129
	s_add_i32 s27, s39, 0x2000
	s_cmpk_lg_i32 s39, 0x6000
	s_cselect_b32 s38, s27, 0
	v_lshl_add_u64 v[82:83], v[146:147], 0, s[12:13]
	s_add_i32 s27, s25, s35
	s_mov_b32 m0, s27
	s_nop 0
	global_load_lds_dwordx4 v[82:83], off
	v_lshl_add_u64 v[148:149], v[148:149], 0, s[8:9]
	s_add_i32 s27, s38, s34
	s_mov_b32 m0, s27
	s_nop 0
	global_load_lds_dwordx4 v[148:149], off
	v_add_u32_e32 v161, s25, v3
	ds_read_b64_tr_b16 v[206:207], v161 offset:32768
	ds_read_b64_tr_b16 v[208:209], v161 offset:33280
	s_waitcnt lgkmcnt(9)
	v_mfma_f32_32x32x16_bf16 v[98:113], v[94:97], v[182:185], v[66:81]
	v_add_f32_e32 v82, v130, v131
	v_add_f32_e32 v82, v132, v82
	v_add_f32_e32 v82, v133, v82
	v_add_f32_e32 v82, v134, v82
	v_add_f32_e32 v82, v135, v82
	v_cvt_pk_bf16_f32 v178, v130, v131
	v_cvt_pk_bf16_f32 v179, v132, v133
	ds_read_b64_tr_b16 v[130:131], v161 offset:36864
	ds_read_b64_tr_b16 v[132:133], v161 offset:37376
	v_add_f32_e32 v82, v136, v82
	v_add_f32_e32 v82, v137, v82
	v_add_f32_e32 v82, v138, v82
	v_add_f32_e32 v162, v139, v82
	s_waitcnt lgkmcnt(10)
	v_mfma_f32_32x32x16_bf16 v[82:97], v[152:155], v[182:185], v[66:81]
	v_cvt_pk_bf16_f32 v180, v134, v135
	v_cvt_pk_bf16_f32 v181, v136, v137
	ds_read_b64_tr_b16 v[134:135], v161 offset:33792
	ds_read_b64_tr_b16 v[136:137], v161 offset:34304
	s_waitcnt lgkmcnt(11)
	v_mfma_f32_32x32x16_bf16 v[98:113], v[156:159], v[174:177], v[98:113]
	v_add_f32_e32 v152, v140, v162
	v_add_f32_e32 v152, v141, v152
	v_add_f32_e32 v152, v142, v152
	v_add_f32_e32 v152, v143, v152
	v_cvt_pk_bf16_f32 v170, v138, v139
	v_cvt_pk_bf16_f32 v171, v140, v141
	ds_read_b64_tr_b16 v[138:139], v161 offset:37888
	ds_read_b64_tr_b16 v[140:141], v161 offset:38400
	s_waitcnt lgkmcnt(12)
	v_mfma_f32_32x32x16_bf16 v[82:97], v[186:189], v[174:177], v[82:97]
	v_add_f32_e32 v152, v144, v152
	v_add_f32_e32 v152, v145, v152
	v_add_f32_e32 v152, v114, v152
	v_add_f32_e32 v152, v115, v152
	v_cvt_pk_bf16_f32 v172, v142, v143
	v_cvt_pk_bf16_f32 v173, v144, v145
	ds_read_b64_tr_b16 v[142:143], v161 offset:34816
	ds_read_b64_tr_b16 v[144:145], v161 offset:35328
	s_waitcnt lgkmcnt(13)
	v_mfma_f32_32x32x16_bf16 v[98:113], v[190:193], v[12:15], v[98:113]
	v_add_f32_e32 v152, v116, v152
	v_add_f32_e32 v152, v117, v152
	v_add_f32_e32 v152, v118, v152
	v_add_f32_e32 v156, v119, v152
	v_cvt_pk_bf16_f32 v166, v114, v115
	v_cvt_pk_bf16_f32 v167, v116, v117
	ds_read_b64_tr_b16 v[152:153], v161 offset:38912
	ds_read_b64_tr_b16 v[154:155], v161 offset:39424
	s_waitcnt lgkmcnt(14)
	v_mfma_f32_32x32x16_bf16 v[82:97], v[194:197], v[12:15], v[82:97]
	v_add_f32_e32 v114, v120, v156
	v_add_f32_e32 v114, v121, v114
	v_add_f32_e32 v114, v122, v114
	v_add_f32_e32 v114, v123, v114
	v_cvt_pk_bf16_f32 v168, v118, v119
	v_cvt_pk_bf16_f32 v169, v120, v121
	ds_read_b64_tr_b16 v[118:119], v161 offset:35840
	ds_read_b64_tr_b16 v[120:121], v161 offset:36352
	s_waitcnt lgkmcnt(14)
	v_mfma_f32_32x32x16_bf16 v[98:113], v[198:201], v[8:11], v[98:113]
	v_add_f32_e32 v114, v124, v114
	v_add_f32_e32 v114, v125, v114
	v_add_f32_e32 v114, v126, v114
	v_add_f32_e32 v114, v127, v114
	v_cvt_pk_bf16_f32 v162, v122, v123
	v_cvt_pk_bf16_f32 v163, v124, v125
	ds_read_b64_tr_b16 v[122:123], v161 offset:39936
	ds_read_b64_tr_b16 v[124:125], v161 offset:40448
	v_mfma_f32_32x32x16_bf16 v[82:97], v[202:205], v[8:11], v[82:97]
	v_add_f32_e32 v114, v128, v114
	v_add_f32_e32 v114, v129, v114
	v_cvt_pk_bf16_f32 v164, v126, v127
	v_cvt_pk_bf16_f32 v165, v128, v129
	v_add_f32_e32 v219, v160, v114
	s_waitcnt lgkmcnt(14)
	v_mfma_f32_32x32x16_bf16 v[34:49], v[178:181], v[206:209], v[34:49]
	v_exp_f32_e32 v98, v98
	v_exp_f32_e32 v99, v99
	v_exp_f32_e32 v100, v100
	v_exp_f32_e32 v101, v101
	s_waitcnt lgkmcnt(12)
	v_mfma_f32_32x32x16_bf16 v[50:65], v[178:181], v[130:133], v[50:65]
	v_exp_f32_e32 v102, v102
	v_exp_f32_e32 v103, v103
	v_exp_f32_e32 v104, v104
	v_exp_f32_e32 v105, v105
	v_add_u32_e32 v126, s38, v7
	ds_read_b128 v[114:117], v126
	ds_read_b128 v[210:213], v126 offset:512
	s_waitcnt lgkmcnt(12)
	v_mfma_f32_32x32x16_bf16 v[34:49], v[170:173], v[134:137], v[34:49]
	v_exp_f32_e32 v106, v106
	v_exp_f32_e32 v107, v107
	v_exp_f32_e32 v108, v108
	v_exp_f32_e32 v109, v109
	ds_read_b128 v[206:209], v126 offset:2048
	ds_read_b128 v[202:205], v126 offset:2560
	s_waitcnt lgkmcnt(12)
	v_mfma_f32_32x32x16_bf16 v[50:65], v[170:173], v[138:141], v[50:65]
	v_exp_f32_e32 v110, v110
	v_exp_f32_e32 v111, v111
	v_exp_f32_e32 v112, v112
	v_exp_f32_e32 v113, v113
	ds_read_b128 v[198:201], v126 offset:4096
	ds_read_b128 v[194:197], v126 offset:4608
	s_waitcnt lgkmcnt(12)
	v_mfma_f32_32x32x16_bf16 v[34:49], v[166:169], v[142:145], v[34:49]
	v_exp_f32_e32 v82, v82
	v_exp_f32_e32 v83, v83
	v_exp_f32_e32 v84, v84
	v_exp_f32_e32 v85, v85
	ds_read_b128 v[190:193], v126 offset:6144
	ds_read_b128 v[186:189], v126 offset:6656
	s_waitcnt lgkmcnt(12)
	v_mfma_f32_32x32x16_bf16 v[50:65], v[166:169], v[152:155], v[50:65]
	v_exp_f32_e32 v86, v86
	v_exp_f32_e32 v87, v87
	v_exp_f32_e32 v88, v88
	v_exp_f32_e32 v89, v89
	s_waitcnt lgkmcnt(10)
	v_mfma_f32_32x32x16_bf16 v[34:49], v[162:165], v[118:121], v[34:49]
	v_exp_f32_e32 v90, v90
	v_exp_f32_e32 v91, v91
	v_exp_f32_e32 v92, v92
	v_exp_f32_e32 v93, v93
	s_waitcnt lgkmcnt(8)
	v_mfma_f32_32x32x16_bf16 v[50:65], v[162:165], v[122:125], v[50:65]
	v_exp_f32_e32 v94, v94
	v_exp_f32_e32 v95, v95
	v_exp_f32_e32 v96, v96
	v_exp_f32_e32 v97, v97
	s_add_i32 s25, s38, 0x2000
	s_cmpk_lg_i32 s38, 0x6000
	s_cselect_b32 s39, s25, 0
	s_add_i32 s37, s37, 2
	v_lshl_add_u64 v[146:147], v[146:147], 0, s[8:9]
	s_mov_b32 s33, s24
	s_cmpk_gt_u32 s37, 0xf9
	s_waitcnt vmcnt(0) lgkmcnt(0)
	s_barrier
	s_cbranch_scc0 .LBB0_1163
	s_and_b32 s25, s36, 0x3fffffc0
	s_cmp_lg_u32 0, -1
	s_cselect_b32 s27, 0, 0
	s_add_i32 s27, s27, 0x8000
	s_lshl_b32 s25, s25, 2
	v_add3_u32 v218, v151, s27, v150
	s_add_i32 s27, s25, 0
	s_add_i32 s27, s27, 0x10000
	v_lshl_add_u64 v[16:17], v[16:17], 0, s[14:15]
	s_add_i32 s25, s24, s35
	s_mov_b32 s28, m0
	s_mov_b32 m0, s25
	s_nop 0
	global_load_lds_dwordx4 v[16:17], off
	s_mov_b32 m0, s28
	v_lshl_add_u64 v[16:17], v[4:5], 0, s[16:17]
	s_add_i32 s25, s39, s34
	s_mov_b32 s28, m0
	s_mov_b32 m0, s25
	s_nop 0
	global_load_lds_dwordx4 v[16:17], off
	s_mov_b32 m0, s28
	v_add_u32_e32 v16, s24, v3
	ds_read_b64_tr_b16 v[130:131], v16 offset:32768
	ds_read_b64_tr_b16 v[132:133], v16 offset:33280
	v_add_f32_e32 v17, v98, v99
	v_add_f32_e32 v17, v100, v17
	v_add_f32_e32 v17, v101, v17
	v_add_f32_e32 v17, v102, v17
	v_add_f32_e32 v17, v103, v17
	v_cvt_pk_bf16_f32 v178, v98, v99
	v_cvt_pk_bf16_f32 v179, v100, v101
	s_waitcnt lgkmcnt(9)
	v_mfma_f32_32x32x16_bf16 v[146:161], v[114:117], v[182:185], v[66:81]
	ds_read_b64_tr_b16 v[98:99], v16 offset:36864
	ds_read_b64_tr_b16 v[100:101], v16 offset:37376
	v_add_f32_e32 v17, v104, v17
	v_add_f32_e32 v17, v105, v17
	v_add_f32_e32 v17, v106, v17
	v_add_f32_e32 v17, v107, v17
	v_cvt_pk_bf16_f32 v180, v102, v103
	v_cvt_pk_bf16_f32 v181, v104, v105
	s_waitcnt lgkmcnt(10)
	v_mfma_f32_32x32x16_bf16 v[114:129], v[210:213], v[182:185], v[66:81]
	ds_read_b64_tr_b16 v[102:103], v16 offset:33792
	ds_read_b64_tr_b16 v[104:105], v16 offset:34304
	v_add_f32_e32 v17, v108, v17
	v_add_f32_e32 v17, v109, v17
	v_add_f32_e32 v17, v110, v17
	v_add_f32_e32 v17, v111, v17
	v_cvt_pk_bf16_f32 v170, v106, v107
	v_cvt_pk_bf16_f32 v171, v108, v109
	s_waitcnt lgkmcnt(11)
	v_mfma_f32_32x32x16_bf16 v[146:161], v[206:209], v[174:177], v[146:161]
	ds_read_b64_tr_b16 v[106:107], v16 offset:37888
	ds_read_b64_tr_b16 v[108:109], v16 offset:38400
	v_add_f32_e32 v17, v112, v17
	v_add_f32_e32 v17, v113, v17
	v_add_f32_e32 v17, v82, v17
	v_add_f32_e32 v17, v83, v17
	v_cvt_pk_bf16_f32 v172, v110, v111
	v_cvt_pk_bf16_f32 v173, v112, v113
	s_waitcnt lgkmcnt(12)
	v_mfma_f32_32x32x16_bf16 v[114:129], v[202:205], v[174:177], v[114:129]
	ds_read_b64_tr_b16 v[110:111], v16 offset:34816
	ds_read_b64_tr_b16 v[112:113], v16 offset:35328
	v_add_f32_e32 v17, v84, v17
	v_add_f32_e32 v17, v85, v17
	v_add_f32_e32 v17, v86, v17
	v_add_f32_e32 v17, v87, v17
	v_cvt_pk_bf16_f32 v166, v82, v83
	v_cvt_pk_bf16_f32 v167, v84, v85
	s_waitcnt lgkmcnt(13)
	v_mfma_f32_32x32x16_bf16 v[146:161], v[198:201], v[12:15], v[146:161]
	ds_read_b64_tr_b16 v[82:83], v16 offset:38912
	ds_read_b64_tr_b16 v[84:85], v16 offset:39424
	v_add_f32_e32 v17, v88, v17
	v_add_f32_e32 v17, v89, v17
	v_add_f32_e32 v17, v90, v17
	v_add_f32_e32 v17, v91, v17
	v_cvt_pk_bf16_f32 v168, v86, v87
	v_cvt_pk_bf16_f32 v169, v88, v89
	s_waitcnt lgkmcnt(14)
	v_mfma_f32_32x32x16_bf16 v[114:129], v[194:197], v[12:15], v[114:129]
	ds_read_b64_tr_b16 v[86:87], v16 offset:35840
	ds_read_b64_tr_b16 v[88:89], v16 offset:36352
	v_add_f32_e32 v17, v92, v17
	v_add_f32_e32 v17, v93, v17
	v_add_f32_e32 v17, v94, v17
	v_add_f32_e32 v17, v95, v17
	v_cvt_pk_bf16_f32 v162, v90, v91
	v_cvt_pk_bf16_f32 v163, v92, v93
	s_waitcnt lgkmcnt(14)
	v_mfma_f32_32x32x16_bf16 v[146:161], v[190:193], v[8:11], v[146:161]
	ds_read_b64_tr_b16 v[90:91], v16 offset:39936
	ds_read_b64_tr_b16 v[92:93], v16 offset:40448
	v_add_f32_e32 v16, v96, v17
	v_add_f32_e32 v16, v97, v16
	v_add_f32_e32 v16, 0, v16
	v_cvt_pk_bf16_f32 v164, v94, v95
	v_cvt_pk_bf16_f32 v165, v96, v97
	v_mfma_f32_32x32x16_bf16 v[114:129], v[186:189], v[8:11], v[114:129]
	v_add_f32_e32 v202, v219, v16
	s_waitcnt lgkmcnt(14)
	v_mfma_f32_32x32x16_bf16 v[34:49], v[178:181], v[130:133], v[34:49]
	s_nop 0
	v_exp_f32_e32 v146, v146
	v_exp_f32_e32 v147, v147
	v_exp_f32_e32 v148, v148
	v_exp_f32_e32 v149, v149
	s_waitcnt lgkmcnt(12)
	v_mfma_f32_32x32x16_bf16 v[50:65], v[178:181], v[98:101], v[50:65]
	v_exp_f32_e32 v150, v150
	v_exp_f32_e32 v151, v151
	v_exp_f32_e32 v152, v152
	v_exp_f32_e32 v153, v153
	v_add_u32_e32 v16, s39, v7
	ds_read_b128 v[94:97], v16
	ds_read_b128 v[98:101], v16 offset:512
	s_waitcnt lgkmcnt(12)
	v_mfma_f32_32x32x16_bf16 v[34:49], v[170:173], v[102:105], v[34:49]
	v_exp_f32_e32 v154, v154
	v_exp_f32_e32 v155, v155
	v_exp_f32_e32 v156, v156
	v_exp_f32_e32 v157, v157
	ds_read_b128 v[102:105], v16 offset:2048
	ds_read_b128 v[186:189], v16 offset:2560
	s_waitcnt lgkmcnt(12)
	v_mfma_f32_32x32x16_bf16 v[50:65], v[170:173], v[106:109], v[50:65]
	v_exp_f32_e32 v158, v158
	v_exp_f32_e32 v159, v159
	v_exp_f32_e32 v160, v160
	v_exp_f32_e32 v161, v161
	ds_read_b128 v[106:109], v16 offset:4096
	ds_read_b128 v[190:193], v16 offset:4608
	s_waitcnt lgkmcnt(12)
	v_mfma_f32_32x32x16_bf16 v[34:49], v[166:169], v[110:113], v[34:49]
	v_exp_f32_e32 v114, v114
	v_exp_f32_e32 v115, v115
	v_exp_f32_e32 v116, v116
	v_exp_f32_e32 v117, v117
	ds_read_b128 v[110:113], v16 offset:6144
	ds_read_b128 v[194:197], v16 offset:6656
	s_waitcnt lgkmcnt(12)
	v_mfma_f32_32x32x16_bf16 v[50:65], v[166:169], v[82:85], v[50:65]
	v_exp_f32_e32 v118, v118
	v_exp_f32_e32 v119, v119
	v_exp_f32_e32 v120, v120
	v_exp_f32_e32 v121, v121
	s_waitcnt lgkmcnt(10)
	v_mfma_f32_32x32x16_bf16 v[34:49], v[162:165], v[86:89], v[34:49]
	v_exp_f32_e32 v122, v122
	v_exp_f32_e32 v123, v123
	v_exp_f32_e32 v124, v124
	v_exp_f32_e32 v125, v125
	s_waitcnt lgkmcnt(8)
	v_mfma_f32_32x32x16_bf16 v[50:65], v[162:165], v[90:93], v[50:65]
	v_exp_f32_e32 v126, v126
	v_exp_f32_e32 v127, v127
	v_exp_f32_e32 v128, v128
	v_exp_f32_e32 v129, v129
	s_add_i32 s24, s39, 0x2000
	s_cmpk_lg_i32 s39, 0x6000
	s_cselect_b32 s25, s24, 0
	v_lshl_add_u64 v[16:17], v[4:5], 0, s[20:21]
	s_add_i32 s24, s25, s34
	s_mov_b32 s28, m0
	s_mov_b32 m0, s24
	s_nop 0
	global_load_lds_dwordx4 v[16:17], off
	s_mov_b32 m0, s28
	v_add_u32_e32 v16, s38, v3
	ds_read_b64_tr_b16 v[198:199], v16 offset:32768
	ds_read_b64_tr_b16 v[200:201], v16 offset:33280
	v_add_f32_e32 v17, v146, v147
	v_add_f32_e32 v17, v148, v17
	v_add_f32_e32 v17, v149, v17
	v_add_f32_e32 v17, v150, v17
	v_add_f32_e32 v17, v151, v17
	v_cvt_pk_bf16_f32 v178, v146, v147
	v_cvt_pk_bf16_f32 v179, v148, v149
	s_waitcnt lgkmcnt(9)
	v_mfma_f32_32x32x16_bf16 v[130:145], v[94:97], v[182:185], v[66:81]
	ds_read_b64_tr_b16 v[146:147], v16 offset:36864
	ds_read_b64_tr_b16 v[148:149], v16 offset:37376
	v_add_f32_e32 v17, v152, v17
	v_add_f32_e32 v17, v153, v17
	v_add_f32_e32 v17, v154, v17
	v_add_f32_e32 v17, v155, v17
	v_cvt_pk_bf16_f32 v180, v150, v151
	v_cvt_pk_bf16_f32 v181, v152, v153
	s_waitcnt lgkmcnt(10)
	v_mfma_f32_32x32x16_bf16 v[82:97], v[98:101], v[182:185], v[66:81]
	ds_read_b64_tr_b16 v[98:99], v16 offset:33792
	ds_read_b64_tr_b16 v[100:101], v16 offset:34304
	v_add_f32_e32 v17, v156, v17
	v_add_f32_e32 v17, v157, v17
	v_add_f32_e32 v17, v158, v17
	v_add_f32_e32 v17, v159, v17
	v_cvt_pk_bf16_f32 v170, v154, v155
	v_cvt_pk_bf16_f32 v171, v156, v157
	s_waitcnt lgkmcnt(11)
	v_mfma_f32_32x32x16_bf16 v[130:145], v[102:105], v[174:177], v[130:145]
	ds_read_b64_tr_b16 v[102:103], v16 offset:37888
	ds_read_b64_tr_b16 v[104:105], v16 offset:38400
	v_add_f32_e32 v17, v160, v17
	v_add_f32_e32 v17, v161, v17
	v_add_f32_e32 v17, v114, v17
	v_add_f32_e32 v17, v115, v17
	v_cvt_pk_bf16_f32 v172, v158, v159
	v_cvt_pk_bf16_f32 v173, v160, v161
	s_waitcnt lgkmcnt(12)
	v_mfma_f32_32x32x16_bf16 v[82:97], v[186:189], v[174:177], v[82:97]
	ds_read_b64_tr_b16 v[150:151], v16 offset:34816
	ds_read_b64_tr_b16 v[152:153], v16 offset:35328
	v_add_f32_e32 v17, v116, v17
	v_add_f32_e32 v17, v117, v17
	v_add_f32_e32 v17, v118, v17
	v_add_f32_e32 v17, v119, v17
	v_cvt_pk_bf16_f32 v166, v114, v115
	v_cvt_pk_bf16_f32 v167, v116, v117
	s_waitcnt lgkmcnt(13)
	v_mfma_f32_32x32x16_bf16 v[130:145], v[106:109], v[12:15], v[130:145]
	ds_read_b64_tr_b16 v[106:107], v16 offset:38912
	ds_read_b64_tr_b16 v[108:109], v16 offset:39424
	v_add_f32_e32 v17, v120, v17
	v_add_f32_e32 v17, v121, v17
	v_add_f32_e32 v17, v122, v17
	v_add_f32_e32 v17, v123, v17
	v_cvt_pk_bf16_f32 v168, v118, v119
	v_cvt_pk_bf16_f32 v169, v120, v121
	s_waitcnt lgkmcnt(14)
	v_mfma_f32_32x32x16_bf16 v[82:97], v[190:193], v[12:15], v[82:97]
	ds_read_b64_tr_b16 v[114:115], v16 offset:35840
	ds_read_b64_tr_b16 v[116:117], v16 offset:36352
	v_add_f32_e32 v17, v124, v17
	v_add_f32_e32 v17, v125, v17
	v_add_f32_e32 v17, v126, v17
	v_add_f32_e32 v17, v127, v17
	v_cvt_pk_bf16_f32 v162, v122, v123
	v_cvt_pk_bf16_f32 v163, v124, v125
	s_waitcnt lgkmcnt(14)
	v_mfma_f32_32x32x16_bf16 v[130:145], v[110:113], v[8:11], v[130:145]
	ds_read_b64_tr_b16 v[110:111], v16 offset:39936
	ds_read_b64_tr_b16 v[112:113], v16 offset:40448
	v_add_f32_e32 v16, v128, v17
	v_add_f32_e32 v16, v129, v16
	v_add_f32_e32 v16, 0, v16
	v_cvt_pk_bf16_f32 v164, v126, v127
	v_cvt_pk_bf16_f32 v165, v128, v129
	v_mfma_f32_32x32x16_bf16 v[82:97], v[194:197], v[8:11], v[82:97]
	v_add_f32_e32 v16, v202, v16
	s_waitcnt lgkmcnt(14)
	v_mfma_f32_32x32x16_bf16 v[34:49], v[178:181], v[198:201], v[34:49]
	s_nop 0
	v_exp_f32_e32 v130, v130
	v_exp_f32_e32 v131, v131
	v_exp_f32_e32 v132, v132
	v_exp_f32_e32 v133, v133
	s_waitcnt lgkmcnt(12)
	v_mfma_f32_32x32x16_bf16 v[50:65], v[178:181], v[146:149], v[50:65]
	v_exp_f32_e32 v134, v134
	v_exp_f32_e32 v135, v135
	v_exp_f32_e32 v136, v136
	v_exp_f32_e32 v137, v137
	v_add_u32_e32 v17, s25, v7
	ds_read_b128 v[146:149], v17
	ds_read_b128 v[154:157], v17 offset:512
	s_waitcnt lgkmcnt(12)
	v_mfma_f32_32x32x16_bf16 v[34:49], v[170:173], v[98:101], v[34:49]
	v_exp_f32_e32 v138, v138
	v_exp_f32_e32 v139, v139
	v_exp_f32_e32 v140, v140
	v_exp_f32_e32 v141, v141
	ds_read_b128 v[158:161], v17 offset:2048
	ds_read_b128 v[186:189], v17 offset:2560
	s_waitcnt lgkmcnt(12)
	v_mfma_f32_32x32x16_bf16 v[50:65], v[170:173], v[102:105], v[50:65]
	v_exp_f32_e32 v142, v142
	v_exp_f32_e32 v143, v143
	v_exp_f32_e32 v144, v144
	v_exp_f32_e32 v145, v145
	ds_read_b128 v[190:193], v17 offset:4096
	ds_read_b128 v[194:197], v17 offset:4608
	s_waitcnt lgkmcnt(12)
	v_mfma_f32_32x32x16_bf16 v[34:49], v[166:169], v[150:153], v[34:49]
	v_exp_f32_e32 v82, v82
	v_exp_f32_e32 v83, v83
	v_exp_f32_e32 v84, v84
	v_exp_f32_e32 v85, v85
	ds_read_b128 v[150:153], v17 offset:6144
	ds_read_b128 v[198:201], v17 offset:6656
	s_waitcnt lgkmcnt(12)
	v_mfma_f32_32x32x16_bf16 v[50:65], v[166:169], v[106:109], v[50:65]
	v_exp_f32_e32 v86, v86
	v_exp_f32_e32 v87, v87
	v_exp_f32_e32 v88, v88
	v_exp_f32_e32 v89, v89
	s_waitcnt lgkmcnt(10)
	v_mfma_f32_32x32x16_bf16 v[34:49], v[162:165], v[114:117], v[34:49]
	v_exp_f32_e32 v90, v90
	v_exp_f32_e32 v91, v91
	v_exp_f32_e32 v92, v92
	v_exp_f32_e32 v93, v93
	s_waitcnt lgkmcnt(8)
	v_mfma_f32_32x32x16_bf16 v[50:65], v[162:165], v[110:113], v[50:65]
	v_exp_f32_e32 v94, v94
	v_exp_f32_e32 v95, v95
	v_exp_f32_e32 v96, v96
	v_exp_f32_e32 v97, v97
	s_waitcnt vmcnt(0) lgkmcnt(0)
	s_barrier
	s_add_i32 s24, s25, 0x2000
	s_cmpk_lg_i32 s25, 0x6000
	s_cselect_b32 s24, s24, 0
	v_lshl_add_u64 v[4:5], v[4:5], 0, s[14:15]
	s_add_i32 s28, s24, s34
	s_mov_b32 s29, m0
	s_mov_b32 m0, s28
	s_nop 0
	global_load_lds_dwordx4 v[4:5], off
	s_mov_b32 m0, s29
	v_add_u32_e32 v4, s39, v3
	ds_read_b64_tr_b16 v[202:203], v4 offset:32768
	ds_read_b64_tr_b16 v[204:205], v4 offset:33280
	v_add_f32_e32 v5, v130, v131
	v_add_f32_e32 v5, v132, v5
	v_add_f32_e32 v5, v133, v5
	v_add_f32_e32 v5, v134, v5
	v_add_f32_e32 v5, v135, v5
	v_cvt_pk_bf16_f32 v178, v130, v131
	v_cvt_pk_bf16_f32 v179, v132, v133
	s_waitcnt lgkmcnt(9)
	v_mfma_f32_32x32x16_bf16 v[114:129], v[146:149], v[182:185], v[66:81]
	ds_read_b64_tr_b16 v[130:131], v4 offset:36864
	ds_read_b64_tr_b16 v[132:133], v4 offset:37376
	v_add_f32_e32 v5, v136, v5
	v_add_f32_e32 v5, v137, v5
	v_add_f32_e32 v5, v138, v5
	v_add_f32_e32 v5, v139, v5
	v_cvt_pk_bf16_f32 v180, v134, v135
	v_cvt_pk_bf16_f32 v181, v136, v137
	s_waitcnt lgkmcnt(10)
	v_mfma_f32_32x32x16_bf16 v[98:113], v[154:157], v[182:185], v[66:81]
	ds_read_b64_tr_b16 v[134:135], v4 offset:33792
	ds_read_b64_tr_b16 v[136:137], v4 offset:34304
	v_add_f32_e32 v5, v140, v5
	v_add_f32_e32 v5, v141, v5
	v_add_f32_e32 v5, v142, v5
	v_add_f32_e32 v5, v143, v5
	v_cvt_pk_bf16_f32 v170, v138, v139
	v_cvt_pk_bf16_f32 v171, v140, v141
	s_waitcnt lgkmcnt(11)
	v_mfma_f32_32x32x16_bf16 v[114:129], v[158:161], v[174:177], v[114:129]
	ds_read_b64_tr_b16 v[138:139], v4 offset:37888
	ds_read_b64_tr_b16 v[140:141], v4 offset:38400
	v_add_f32_e32 v5, v144, v5
	v_add_f32_e32 v5, v145, v5
	v_add_f32_e32 v5, v82, v5
	v_add_f32_e32 v5, v83, v5
	v_cvt_pk_bf16_f32 v172, v142, v143
	v_cvt_pk_bf16_f32 v173, v144, v145
	s_waitcnt lgkmcnt(12)
	v_mfma_f32_32x32x16_bf16 v[98:113], v[186:189], v[174:177], v[98:113]
	ds_read_b64_tr_b16 v[142:143], v4 offset:34816
	ds_read_b64_tr_b16 v[144:145], v4 offset:35328
	v_add_f32_e32 v5, v84, v5
	v_add_f32_e32 v5, v85, v5
	v_add_f32_e32 v5, v86, v5
	v_add_f32_e32 v5, v87, v5
	v_cvt_pk_bf16_f32 v166, v82, v83
	v_cvt_pk_bf16_f32 v167, v84, v85
	s_waitcnt lgkmcnt(13)
	v_mfma_f32_32x32x16_bf16 v[114:129], v[190:193], v[12:15], v[114:129]
	ds_read_b64_tr_b16 v[82:83], v4 offset:38912
	ds_read_b64_tr_b16 v[84:85], v4 offset:39424
	v_add_f32_e32 v5, v88, v5
	v_add_f32_e32 v5, v89, v5
	v_add_f32_e32 v5, v90, v5
	v_add_f32_e32 v5, v91, v5
	v_cvt_pk_bf16_f32 v168, v86, v87
	v_cvt_pk_bf16_f32 v169, v88, v89
	s_waitcnt lgkmcnt(14)
	v_mfma_f32_32x32x16_bf16 v[98:113], v[194:197], v[12:15], v[98:113]
	ds_read_b64_tr_b16 v[86:87], v4 offset:35840
	ds_read_b64_tr_b16 v[88:89], v4 offset:36352
	v_add_f32_e32 v5, v92, v5
	v_add_f32_e32 v5, v93, v5
	v_add_f32_e32 v5, v94, v5
	v_add_f32_e32 v5, v95, v5
	v_cvt_pk_bf16_f32 v162, v90, v91
	v_cvt_pk_bf16_f32 v163, v92, v93
	s_waitcnt lgkmcnt(14)
	v_mfma_f32_32x32x16_bf16 v[114:129], v[150:153], v[8:11], v[114:129]
	ds_read_b64_tr_b16 v[90:91], v4 offset:39936
	ds_read_b64_tr_b16 v[92:93], v4 offset:40448
	v_add_f32_e32 v4, v96, v5
	v_add_f32_e32 v4, v97, v4
	v_add_f32_e32 v4, 0, v4
	v_cvt_pk_bf16_f32 v164, v94, v95
	v_cvt_pk_bf16_f32 v165, v96, v97
	v_mfma_f32_32x32x16_bf16 v[98:113], v[198:201], v[8:11], v[98:113]
	v_add_f32_e32 v4, v16, v4
	s_waitcnt lgkmcnt(14)
	v_mfma_f32_32x32x16_bf16 v[34:49], v[178:181], v[202:205], v[34:49]
	s_nop 0
	v_exp_f32_e32 v114, v114
	v_exp_f32_e32 v115, v115
	v_exp_f32_e32 v116, v116
	v_exp_f32_e32 v117, v117
	s_waitcnt lgkmcnt(12)
	v_mfma_f32_32x32x16_bf16 v[50:65], v[178:181], v[130:133], v[50:65]
	v_exp_f32_e32 v118, v118
	v_exp_f32_e32 v119, v119
	v_exp_f32_e32 v120, v120
	v_exp_f32_e32 v121, v121
	v_add_u32_e32 v5, s24, v7
	ds_read_b128 v[94:97], v5
	s_waitcnt lgkmcnt(11)
	v_mfma_f32_32x32x16_bf16 v[34:49], v[170:173], v[134:137], v[34:49]
	v_exp_f32_e32 v122, v122
	v_exp_f32_e32 v123, v123
	v_exp_f32_e32 v124, v124
	v_exp_f32_e32 v125, v125
	ds_read_b128 v[130:133], v5 offset:2048
	s_waitcnt lgkmcnt(10)
	v_mfma_f32_32x32x16_bf16 v[50:65], v[170:173], v[138:141], v[50:65]
	v_exp_f32_e32 v126, v126
	v_exp_f32_e32 v127, v127
	v_exp_f32_e32 v128, v128
	v_exp_f32_e32 v129, v129
	ds_read_b128 v[134:137], v5 offset:4096
	s_waitcnt lgkmcnt(9)
	v_mfma_f32_32x32x16_bf16 v[34:49], v[166:169], v[142:145], v[34:49]
	v_exp_f32_e32 v98, v98
	v_exp_f32_e32 v99, v99
	v_exp_f32_e32 v100, v100
	v_exp_f32_e32 v101, v101
	ds_read_b128 v[138:141], v5 offset:6144
	s_waitcnt lgkmcnt(8)
	v_mfma_f32_32x32x16_bf16 v[50:65], v[166:169], v[82:85], v[50:65]
	v_exp_f32_e32 v102, v102
	v_exp_f32_e32 v103, v103
	v_exp_f32_e32 v104, v104
	v_exp_f32_e32 v105, v105
	s_waitcnt lgkmcnt(6)
	v_mfma_f32_32x32x16_bf16 v[34:49], v[162:165], v[86:89], v[34:49]
	v_exp_f32_e32 v106, v106
	v_exp_f32_e32 v107, v107
	v_exp_f32_e32 v108, v108
	v_exp_f32_e32 v109, v109
	s_waitcnt lgkmcnt(4)
	v_mfma_f32_32x32x16_bf16 v[50:65], v[162:165], v[90:93], v[50:65]
	v_exp_f32_e32 v110, v110
	v_exp_f32_e32 v111, v111
	v_exp_f32_e32 v112, v112
	v_exp_f32_e32 v113, v113
	v_add_u32_e32 v3, s25, v3
	ds_read_b64_tr_b16 v[82:83], v3 offset:32768
	ds_read_b64_tr_b16 v[84:85], v3 offset:33280
	v_add_f32_e32 v5, v114, v115
	v_add_f32_e32 v5, v116, v5
	v_add_f32_e32 v5, v117, v5
	v_add_f32_e32 v5, v118, v5
	v_add_f32_e32 v5, v119, v5
	v_cvt_pk_bf16_f32 v178, v114, v115
	v_cvt_pk_bf16_f32 v179, v116, v117
	s_waitcnt lgkmcnt(5)
	v_mfma_f32_32x32x16_bf16 v[66:81], v[94:97], v[182:185], v[66:81]
	ds_read_b64_tr_b16 v[86:87], v3 offset:36864
	ds_read_b64_tr_b16 v[88:89], v3 offset:37376
	v_add_f32_e32 v5, v120, v5
	v_add_f32_e32 v5, v121, v5
	v_add_f32_e32 v5, v122, v5
	v_add_f32_e32 v5, v123, v5
	v_cvt_pk_bf16_f32 v180, v118, v119
	v_cvt_pk_bf16_f32 v181, v120, v121
	ds_read_b64_tr_b16 v[90:91], v3 offset:33792
	ds_read_b64_tr_b16 v[92:93], v3 offset:34304
	v_add_f32_e32 v5, v124, v5
	v_add_f32_e32 v5, v125, v5
	v_add_f32_e32 v5, v126, v5
	v_add_f32_e32 v5, v127, v5
	v_cvt_pk_bf16_f32 v170, v122, v123
	v_cvt_pk_bf16_f32 v171, v124, v125
	s_waitcnt lgkmcnt(8)
	v_mfma_f32_32x32x16_bf16 v[66:81], v[130:133], v[174:177], v[66:81]
	ds_read_b64_tr_b16 v[94:95], v3 offset:37888
	ds_read_b64_tr_b16 v[96:97], v3 offset:38400
	v_add_f32_e32 v5, v128, v5
	v_add_f32_e32 v5, v129, v5
	v_add_f32_e32 v5, v98, v5
	v_add_f32_e32 v5, v99, v5
	v_cvt_pk_bf16_f32 v172, v126, v127
	v_cvt_pk_bf16_f32 v173, v128, v129
	ds_read_b64_tr_b16 v[114:115], v3 offset:34816
	ds_read_b64_tr_b16 v[116:117], v3 offset:35328
	v_add_f32_e32 v5, v100, v5
	v_add_f32_e32 v5, v101, v5
	v_add_f32_e32 v5, v102, v5
	v_add_f32_e32 v5, v103, v5
	v_cvt_pk_bf16_f32 v166, v98, v99
	v_cvt_pk_bf16_f32 v167, v100, v101
	s_waitcnt lgkmcnt(11)
	v_mfma_f32_32x32x16_bf16 v[66:81], v[134:137], v[12:15], v[66:81]
	ds_read_b64_tr_b16 v[98:99], v3 offset:38912
	ds_read_b64_tr_b16 v[100:101], v3 offset:39424
	v_add_f32_e32 v5, v104, v5
	v_add_f32_e32 v5, v105, v5
	v_add_f32_e32 v5, v106, v5
	v_add_f32_e32 v5, v107, v5
	v_cvt_pk_bf16_f32 v168, v102, v103
	v_cvt_pk_bf16_f32 v169, v104, v105
	ds_read_b64_tr_b16 v[102:103], v3 offset:35840
	ds_read_b64_tr_b16 v[104:105], v3 offset:36352
	v_add_f32_e32 v5, v108, v5
	v_add_f32_e32 v5, v109, v5
	v_add_f32_e32 v5, v110, v5
	v_add_f32_e32 v5, v111, v5
	v_cvt_pk_bf16_f32 v162, v106, v107
	v_cvt_pk_bf16_f32 v163, v108, v109
	s_waitcnt lgkmcnt(14)
	v_mfma_f32_32x32x16_bf16 v[66:81], v[138:141], v[8:11], v[66:81]
	ds_read_b64_tr_b16 v[106:107], v3 offset:39936
	ds_read_b64_tr_b16 v[108:109], v3 offset:40448
	v_add_f32_e32 v3, v112, v5
	v_add_f32_e32 v3, v113, v3
	v_add_f32_e32 v3, 0, v3
	v_cvt_pk_bf16_f32 v164, v110, v111
	v_cvt_pk_bf16_f32 v165, v112, v113
	s_nop 0
	v_add_f32_e32 v110, v4, v3
	s_waitcnt lgkmcnt(14)
	v_mfma_f32_32x32x16_bf16 v[34:49], v[178:181], v[82:85], v[34:49]
	s_nop 0
	v_exp_f32_e32 v66, v66
	v_exp_f32_e32 v67, v67
	v_exp_f32_e32 v68, v68
	v_exp_f32_e32 v69, v69
	v_mov_b32_e32 v74, v6
	v_mov_b32_e32 v75, v6
	v_mov_b32_e32 v76, v6
	v_mov_b32_e32 v77, v6
	v_mov_b32_e32 v78, v6
	v_mov_b32_e32 v79, v6
	v_mov_b32_e32 v80, v6
	v_mov_b32_e32 v81, v6
	s_waitcnt lgkmcnt(12)
	v_mfma_f32_32x32x16_bf16 v[50:65], v[178:181], v[86:89], v[50:65]
	v_exp_f32_e32 v70, v70
	v_exp_f32_e32 v71, v71
	v_exp_f32_e32 v72, v72
	v_exp_f32_e32 v73, v73
	s_waitcnt lgkmcnt(10)
	v_mfma_f32_32x32x16_bf16 v[34:49], v[170:173], v[90:93], v[34:49]
	v_exp_f32_e32 v74, v74
	v_exp_f32_e32 v75, v75
	v_exp_f32_e32 v76, v76
	v_exp_f32_e32 v77, v77
	s_waitcnt lgkmcnt(8)
	v_mfma_f32_32x32x16_bf16 v[50:65], v[170:173], v[94:97], v[50:65]
	v_exp_f32_e32 v78, v78
	v_exp_f32_e32 v79, v79
	v_exp_f32_e32 v80, v80
	v_exp_f32_e32 v81, v81
	s_waitcnt lgkmcnt(6)
	v_mfma_f32_32x32x16_bf16 v[34:49], v[166:169], v[114:117], v[34:49]
	v_mov_b32_e32 v16, v6
	v_mov_b32_e32 v17, v6
	v_mov_b32_e32 v3, v2
	v_mov_b32_e32 v4, v2
	v_mov_b32_e32 v5, v2
	v_mov_b32_e32 v7, v6
	v_mov_b32_e32 v8, v6
	v_mov_b32_e32 v9, v6
	v_mov_b32_e32 v10, v6
	v_mov_b32_e32 v11, v6
	v_mov_b32_e32 v12, v6
	v_mov_b32_e32 v13, v6
	v_mov_b32_e32 v14, v6
	v_mov_b32_e32 v15, v6
	v_mov_b64_e32 v[96:97], v[16:17]
	v_mov_b64_e32 v[94:95], v[14:15]
	v_mov_b64_e32 v[92:93], v[12:13]
	v_mov_b64_e32 v[90:91], v[10:11]
	v_mov_b64_e32 v[88:89], v[8:9]
	v_mov_b64_e32 v[86:87], v[6:7]
	v_mov_b64_e32 v[84:85], v[4:5]
	v_mov_b64_e32 v[82:83], v[2:3]
	s_waitcnt lgkmcnt(4)
	v_mfma_f32_32x32x16_bf16 v[50:65], v[166:169], v[98:101], v[50:65]
	v_exp_f32_e32 v86, v86
	v_exp_f32_e32 v87, v87
	v_exp_f32_e32 v88, v88
	v_exp_f32_e32 v89, v89
	s_waitcnt lgkmcnt(2)
	v_mfma_f32_32x32x16_bf16 v[34:49], v[162:165], v[102:105], v[34:49]
	v_exp_f32_e32 v90, v90
	v_exp_f32_e32 v91, v91
	v_exp_f32_e32 v92, v92
	v_exp_f32_e32 v93, v93
	s_waitcnt lgkmcnt(0)
	v_mfma_f32_32x32x16_bf16 v[50:65], v[162:165], v[106:109], v[50:65]
	v_exp_f32_e32 v94, v94
	v_exp_f32_e32 v95, v95
	v_exp_f32_e32 v96, v96
	v_exp_f32_e32 v97, v97
	v_add_f32_e32 v3, v66, v67
	v_add_f32_e32 v3, v68, v3
	v_add_f32_e32 v3, v69, v3
	v_add_f32_e32 v3, v70, v3
	v_add_f32_e32 v3, v71, v3
	v_add_f32_e32 v3, v72, v3
	v_add_f32_e32 v3, v73, v3
	v_add_f32_e32 v3, v74, v3
	v_add_f32_e32 v3, v75, v3
	v_add_f32_e32 v3, v76, v3
	v_add_f32_e32 v3, v77, v3
	v_add_f32_e32 v3, v78, v3
	v_add_f32_e32 v3, v79, v3
	v_add_f32_e32 v3, v80, v3
	v_add_f32_e32 v3, v81, v3
	v_add_f32_e32 v3, v82, v3
	v_add_f32_e32 v3, v83, v3
	v_add_f32_e32 v3, v84, v3
	v_add_f32_e32 v3, v85, v3
	v_add_f32_e32 v3, v86, v3
	v_add_f32_e32 v3, v87, v3
	v_add_f32_e32 v3, v88, v3
	v_add_f32_e32 v3, v89, v3
	v_add_f32_e32 v3, v90, v3
	v_add_f32_e32 v3, v91, v3
	v_add_f32_e32 v3, v92, v3
	v_add_f32_e32 v3, v93, v3
	v_add_f32_e32 v3, v94, v3
	v_add_f32_e32 v3, v95, v3
	s_waitcnt vmcnt(0) lgkmcnt(0)
	s_barrier
	v_add_f32_e32 v3, v96, v3
	v_add_f32_e32 v3, v97, v3
	v_add_f32_e32 v3, v110, v3
	v_cvt_pk_bf16_f32 v8, v66, v67
	v_cvt_pk_bf16_f32 v9, v68, v69
	v_cvt_pk_bf16_f32 v10, v70, v71
	v_cvt_pk_bf16_f32 v11, v72, v73
	v_cvt_pk_bf16_f32 v12, v74, v75
	v_cvt_pk_bf16_f32 v13, v76, v77
	v_cvt_pk_bf16_f32 v14, v78, v79
	v_cvt_pk_bf16_f32 v15, v80, v81
	v_cvt_pk_bf16_f32 v98, v82, v83
	v_cvt_pk_bf16_f32 v99, v84, v85
	v_cvt_pk_bf16_f32 v100, v86, v87
	v_cvt_pk_bf16_f32 v101, v88, v89
	v_cvt_pk_bf16_f32 v102, v90, v91
	v_cvt_pk_bf16_f32 v103, v92, v93
	v_cvt_pk_bf16_f32 v104, v94, v95
	v_cvt_pk_bf16_f32 v105, v96, v97
	v_add3_u32 v4, v218, v217, s24
	ds_read_b64_tr_b16 v[66:67],v4 offset:0
	ds_read_b64_tr_b16 v[68:69],v4 offset:512
	ds_read_b64_tr_b16 v[70:71],v4 offset:1024
	ds_read_b64_tr_b16 v[72:73],v4 offset:1536
	ds_read_b64_tr_b16 v[74:75],v4 offset:2048
	ds_read_b64_tr_b16 v[76:77],v4 offset:2560
	ds_read_b64_tr_b16 v[78:79],v4 offset:3072
	ds_read_b64_tr_b16 v[80:81],v4 offset:3584
	s_waitcnt lgkmcnt(0)
	s_nop 0
	v_mfma_f32_32x32x16_bf16 v[34:49], v[8:11], v[66:69], v[34:49]
	ds_read_b64_tr_b16 v[66:67],v4 offset:4096
	ds_read_b64_tr_b16 v[68:69],v4 offset:4608
	v_mfma_f32_32x32x16_bf16 v[34:49], v[12:15], v[70:73], v[34:49]
	ds_read_b64_tr_b16 v[70:71],v4 offset:5120
	ds_read_b64_tr_b16 v[72:73],v4 offset:5632
	v_mfma_f32_32x32x16_bf16 v[34:49], v[98:101], v[74:77], v[34:49]
	ds_read_b64_tr_b16 v[74:75],v4 offset:6144
	ds_read_b64_tr_b16 v[76:77],v4 offset:6656
	ds_read_b64_tr_b16 v[82:83],v4 offset:7168
	ds_read_b64_tr_b16 v[84:85],v4 offset:7680
	s_waitcnt lgkmcnt(0)
	v_mfma_f32_32x32x16_bf16 v[34:49], v[102:105], v[78:81], v[34:49]
	v_mfma_f32_32x32x16_bf16 v[50:65], v[8:11], v[66:69], v[50:65]
	v_mov_b32_e32 v4, v3
	s_nop 1
	v_permlane32_swap_b32_e32 v3, v4
	v_cmp_gt_u32_e32 vcc, 32, v1
	v_mfma_f32_32x32x16_bf16 v[50:65], v[12:15], v[70:73], v[50:65]
	v_mfma_f32_32x32x16_bf16 v[50:65], v[98:101], v[74:77], v[50:65]
	v_mfma_f32_32x32x16_bf16 v[50:65], v[102:105], v[82:85], v[50:65]
	s_and_saveexec_b64 s[24:25], vcc
	s_cbranch_execz .LBB0_1117
	v_lshl_add_u32 v5, v215, 2, s27
	v_add_f32_e32 v3, v3, v4
	ds_write_b32 v5, v3 offset:128
	s_branch .LBB0_1117

.LBB0_1688:
	s_waitcnt lgkmcnt(0)
	s_barrier
	s_setprio 1
	s_waitcnt lgkmcnt(0)
	v_mfma_f32_16x16x32_bf16 v[6:9], v[158:161], v[186:189], v[6:9]
	v_mfma_f32_16x16x32_bf16 v[10:13], v[166:169], v[186:189], v[10:13]
	v_mfma_f32_16x16x32_bf16 v[14:17], v[158:161], v[178:181], v[14:17]
	v_mfma_f32_16x16x32_bf16 v[18:21], v[166:169], v[178:181], v[18:21]
	v_mfma_f32_16x16x32_bf16 v[22:25], v[158:161], v[106:109], v[22:25]
	v_mfma_f32_16x16x32_bf16 v[26:29], v[166:169], v[106:109], v[26:29]
	v_mfma_f32_16x16x32_bf16 v[30:33], v[158:161], v[98:101], v[30:33]
	v_mfma_f32_16x16x32_bf16 v[34:37], v[166:169], v[98:101], v[34:37]
	v_mfma_f32_16x16x32_bf16 v[6:9], v[162:165], v[190:193], v[6:9]
	v_mfma_f32_16x16x32_bf16 v[10:13], v[170:173], v[190:193], v[10:13]
	v_mfma_f32_16x16x32_bf16 v[14:17], v[162:165], v[182:185], v[14:17]
	v_mfma_f32_16x16x32_bf16 v[18:21], v[170:173], v[182:185], v[18:21]
	v_mfma_f32_16x16x32_bf16 v[22:25], v[162:165], v[174:177], v[22:25]
	v_mfma_f32_16x16x32_bf16 v[26:29], v[170:173], v[174:177], v[26:29]
	v_mfma_f32_16x16x32_bf16 v[30:33], v[162:165], v[102:105], v[30:33]
	v_mfma_f32_16x16x32_bf16 v[34:37], v[170:173], v[102:105], v[34:37]
	s_setprio 0
	s_setprio 1
	v_mfma_f32_16x16x32_bf16 v[38:41], v[142:145], v[186:189], v[38:41]
	v_mfma_f32_16x16x32_bf16 v[42:45], v[150:153], v[186:189], v[42:45]
	v_mfma_f32_16x16x32_bf16 v[46:49], v[142:145], v[178:181], v[46:49]
	v_mfma_f32_16x16x32_bf16 v[50:53], v[150:153], v[178:181], v[50:53]
	v_mfma_f32_16x16x32_bf16 v[54:57], v[142:145], v[106:109], v[54:57]
	v_mfma_f32_16x16x32_bf16 v[58:61], v[150:153], v[106:109], v[58:61]
	v_mfma_f32_16x16x32_bf16 v[62:65], v[142:145], v[98:101], v[62:65]
	v_mfma_f32_16x16x32_bf16 v[70:73], v[150:153], v[98:101], v[70:73]
	v_mfma_f32_16x16x32_bf16 v[38:41], v[146:149], v[190:193], v[38:41]
	v_mfma_f32_16x16x32_bf16 v[42:45], v[154:157], v[190:193], v[42:45]
	v_mfma_f32_16x16x32_bf16 v[46:49], v[146:149], v[182:185], v[46:49]
	v_mfma_f32_16x16x32_bf16 v[50:53], v[154:157], v[182:185], v[50:53]
	v_mfma_f32_16x16x32_bf16 v[54:57], v[146:149], v[174:177], v[54:57]
	v_mfma_f32_16x16x32_bf16 v[58:61], v[154:157], v[174:177], v[58:61]
	v_mfma_f32_16x16x32_bf16 v[62:65], v[146:149], v[102:105], v[62:65]
	v_mfma_f32_16x16x32_bf16 v[70:73], v[154:157], v[102:105], v[70:73]
	s_setprio 0
	s_add_i32 s90, s90, 2
	s_add_u32 s56, s56, 0x100
	s_addc_u32 s57, s57, 0
	s_cmp_gt_u32 s90, 13
	s_barrier
	s_cbranch_scc1 .LBB0_1701

.LBB0_1759:
	s_waitcnt lgkmcnt(0)
	s_barrier
	s_setprio 1
	s_waitcnt lgkmcnt(0)
	v_mfma_f32_16x16x32_bf16 v[62:65], v[154:157], v[186:189], v[62:65]
	v_mfma_f32_16x16x32_bf16 v[54:57], v[146:149], v[186:189], v[54:57]
	v_mfma_f32_16x16x32_bf16 v[46:49], v[154:157], v[178:181], v[46:49]
	v_mfma_f32_16x16x32_bf16 v[38:41], v[146:149], v[178:181], v[38:41]
	v_mfma_f32_16x16x32_bf16 v[30:33], v[154:157], v[170:173], v[30:33]
	v_mfma_f32_16x16x32_bf16 v[22:25], v[146:149], v[170:173], v[22:25]
	v_mfma_f32_16x16x32_bf16 v[14:17], v[154:157], v[162:165], v[14:17]
	v_mfma_f32_16x16x32_bf16 v[6:9], v[146:149], v[162:165], v[6:9]
	v_mfma_f32_16x16x32_bf16 v[62:65], v[158:161], v[190:193], v[62:65]
	v_mfma_f32_16x16x32_bf16 v[54:57], v[150:153], v[190:193], v[54:57]
	v_mfma_f32_16x16x32_bf16 v[46:49], v[158:161], v[182:185], v[46:49]
	v_mfma_f32_16x16x32_bf16 v[38:41], v[150:153], v[182:185], v[38:41]
	v_mfma_f32_16x16x32_bf16 v[30:33], v[158:161], v[174:177], v[30:33]
	v_mfma_f32_16x16x32_bf16 v[22:25], v[150:153], v[174:177], v[22:25]
	v_mfma_f32_16x16x32_bf16 v[14:17], v[158:161], v[166:169], v[14:17]
	v_mfma_f32_16x16x32_bf16 v[6:9], v[150:153], v[166:169], v[6:9]
	s_setprio 0
	s_setprio 1
	v_mfma_f32_16x16x32_bf16 v[58:61], v[138:141], v[186:189], v[58:61]
	v_mfma_f32_16x16x32_bf16 v[50:53], v[130:133], v[186:189], v[50:53]
	v_mfma_f32_16x16x32_bf16 v[42:45], v[138:141], v[178:181], v[42:45]
	v_mfma_f32_16x16x32_bf16 v[34:37], v[130:133], v[178:181], v[34:37]
	v_mfma_f32_16x16x32_bf16 v[26:29], v[138:141], v[170:173], v[26:29]
	v_mfma_f32_16x16x32_bf16 v[18:21], v[130:133], v[170:173], v[18:21]
	v_mfma_f32_16x16x32_bf16 v[10:13], v[138:141], v[162:165], v[10:13]
	v_mfma_f32_16x16x32_bf16 v[2:5], v[130:133], v[162:165], v[2:5]
	v_mfma_f32_16x16x32_bf16 v[58:61], v[142:145], v[190:193], v[58:61]
	v_mfma_f32_16x16x32_bf16 v[50:53], v[134:137], v[190:193], v[50:53]
	v_mfma_f32_16x16x32_bf16 v[42:45], v[142:145], v[182:185], v[42:45]
	v_mfma_f32_16x16x32_bf16 v[34:37], v[134:137], v[182:185], v[34:37]
	v_mfma_f32_16x16x32_bf16 v[26:29], v[142:145], v[174:177], v[26:29]
	v_mfma_f32_16x16x32_bf16 v[18:21], v[134:137], v[174:177], v[18:21]
	v_mfma_f32_16x16x32_bf16 v[10:13], v[142:145], v[166:169], v[10:13]
	v_mfma_f32_16x16x32_bf16 v[2:5], v[134:137], v[166:169], v[2:5]
	s_setprio 0
	s_add_i32 s94, s94, 2
	s_add_u32 s56, s56, 0x100
	s_addc_u32 s57, s57, 0
	s_cmp_gt_u32 s94, 13
	s_barrier
	s_cbranch_scc1 .LBB0_1772

.LBB0_1927:
	s_waitcnt lgkmcnt(0)
	s_barrier
	s_setprio 1
	s_waitcnt lgkmcnt(0)
	v_mfma_f32_16x16x32_bf16 v[58:61], v[146:149], v[186:189], v[58:61]
	v_mfma_f32_16x16x32_bf16 v[50:53], v[154:157], v[186:189], v[50:53]
	v_mfma_f32_16x16x32_bf16 v[42:45], v[146:149], v[178:181], v[42:45]
	v_mfma_f32_16x16x32_bf16 v[34:37], v[154:157], v[178:181], v[34:37]
	v_mfma_f32_16x16x32_bf16 v[26:29], v[146:149], v[170:173], v[26:29]
	v_mfma_f32_16x16x32_bf16 v[18:21], v[154:157], v[170:173], v[18:21]
	v_mfma_f32_16x16x32_bf16 v[10:13], v[146:149], v[162:165], v[10:13]
	v_mfma_f32_16x16x32_bf16 v[2:5], v[154:157], v[162:165], v[2:5]
	v_mfma_f32_16x16x32_bf16 v[58:61], v[150:153], v[190:193], v[58:61]
	v_mfma_f32_16x16x32_bf16 v[50:53], v[158:161], v[190:193], v[50:53]
	v_mfma_f32_16x16x32_bf16 v[42:45], v[150:153], v[182:185], v[42:45]
	v_mfma_f32_16x16x32_bf16 v[34:37], v[158:161], v[182:185], v[34:37]
	v_mfma_f32_16x16x32_bf16 v[26:29], v[150:153], v[174:177], v[26:29]
	v_mfma_f32_16x16x32_bf16 v[18:21], v[158:161], v[174:177], v[18:21]
	v_mfma_f32_16x16x32_bf16 v[10:13], v[150:153], v[166:169], v[10:13]
	v_mfma_f32_16x16x32_bf16 v[2:5], v[158:161], v[166:169], v[2:5]
	s_setprio 0
	s_setprio 1
	v_mfma_f32_16x16x32_bf16 v[62:65], v[130:133], v[186:189], v[62:65]
	v_mfma_f32_16x16x32_bf16 v[54:57], v[138:141], v[186:189], v[54:57]
	v_mfma_f32_16x16x32_bf16 v[46:49], v[130:133], v[178:181], v[46:49]
	v_mfma_f32_16x16x32_bf16 v[38:41], v[138:141], v[178:181], v[38:41]
	v_mfma_f32_16x16x32_bf16 v[30:33], v[130:133], v[170:173], v[30:33]
	v_mfma_f32_16x16x32_bf16 v[22:25], v[138:141], v[170:173], v[22:25]
	v_mfma_f32_16x16x32_bf16 v[14:17], v[130:133], v[162:165], v[14:17]
	v_mfma_f32_16x16x32_bf16 v[6:9], v[138:141], v[162:165], v[6:9]
	v_mfma_f32_16x16x32_bf16 v[62:65], v[134:137], v[190:193], v[62:65]
	v_mfma_f32_16x16x32_bf16 v[54:57], v[142:145], v[190:193], v[54:57]
	v_mfma_f32_16x16x32_bf16 v[46:49], v[134:137], v[182:185], v[46:49]
	v_mfma_f32_16x16x32_bf16 v[38:41], v[142:145], v[182:185], v[38:41]
	v_mfma_f32_16x16x32_bf16 v[30:33], v[134:137], v[174:177], v[30:33]
	v_mfma_f32_16x16x32_bf16 v[22:25], v[142:145], v[174:177], v[22:25]
	v_mfma_f32_16x16x32_bf16 v[14:17], v[134:137], v[166:169], v[14:17]
	v_mfma_f32_16x16x32_bf16 v[6:9], v[142:145], v[166:169], v[6:9]
	s_setprio 0
	s_add_i32 s94, s94, 2
	s_add_u32 s44, s44, 0x100
	s_addc_u32 s45, s45, 0
	s_cmp_gt_u32 s94, 13
	s_barrier
	s_cbranch_scc1 .LBB0_1940

.LBB0_2052:
	s_waitcnt lgkmcnt(0)
	s_barrier
	s_setprio 1
	s_waitcnt lgkmcnt(0)
	v_mfma_f32_16x16x32_bf16 v[2:5], v[146:149], v[186:189], v[2:5]
	v_mfma_f32_16x16x32_bf16 v[6:9], v[154:157], v[186:189], v[6:9]
	v_mfma_f32_16x16x32_bf16 v[10:13], v[146:149], v[178:181], v[10:13]
	v_mfma_f32_16x16x32_bf16 v[14:17], v[154:157], v[178:181], v[14:17]
	v_mfma_f32_16x16x32_bf16 v[18:21], v[146:149], v[170:173], v[18:21]
	v_mfma_f32_16x16x32_bf16 v[22:25], v[154:157], v[170:173], v[22:25]
	v_mfma_f32_16x16x32_bf16 v[26:29], v[146:149], v[162:165], v[26:29]
	v_mfma_f32_16x16x32_bf16 v[30:33], v[154:157], v[162:165], v[30:33]
	v_mfma_f32_16x16x32_bf16 v[2:5], v[150:153], v[190:193], v[2:5]
	v_mfma_f32_16x16x32_bf16 v[6:9], v[158:161], v[190:193], v[6:9]
	v_mfma_f32_16x16x32_bf16 v[10:13], v[150:153], v[182:185], v[10:13]
	v_mfma_f32_16x16x32_bf16 v[14:17], v[158:161], v[182:185], v[14:17]
	v_mfma_f32_16x16x32_bf16 v[18:21], v[150:153], v[174:177], v[18:21]
	v_mfma_f32_16x16x32_bf16 v[22:25], v[158:161], v[174:177], v[22:25]
	v_mfma_f32_16x16x32_bf16 v[26:29], v[150:153], v[166:169], v[26:29]
	v_mfma_f32_16x16x32_bf16 v[30:33], v[158:161], v[166:169], v[30:33]
	s_setprio 0
	s_setprio 1
	v_mfma_f32_16x16x32_bf16 v[34:37], v[130:133], v[186:189], v[34:37]
	v_mfma_f32_16x16x32_bf16 v[38:41], v[138:141], v[186:189], v[38:41]
	v_mfma_f32_16x16x32_bf16 v[42:45], v[130:133], v[178:181], v[42:45]
	v_mfma_f32_16x16x32_bf16 v[46:49], v[138:141], v[178:181], v[46:49]
	v_mfma_f32_16x16x32_bf16 v[50:53], v[130:133], v[170:173], v[50:53]
	v_mfma_f32_16x16x32_bf16 v[54:57], v[138:141], v[170:173], v[54:57]
	v_mfma_f32_16x16x32_bf16 v[58:61], v[130:133], v[162:165], v[58:61]
	v_mfma_f32_16x16x32_bf16 v[62:65], v[138:141], v[162:165], v[62:65]
	v_mfma_f32_16x16x32_bf16 v[34:37], v[134:137], v[190:193], v[34:37]
	v_mfma_f32_16x16x32_bf16 v[38:41], v[142:145], v[190:193], v[38:41]
	v_mfma_f32_16x16x32_bf16 v[42:45], v[134:137], v[182:185], v[42:45]
	v_mfma_f32_16x16x32_bf16 v[46:49], v[142:145], v[182:185], v[46:49]
	v_mfma_f32_16x16x32_bf16 v[50:53], v[134:137], v[174:177], v[50:53]
	v_mfma_f32_16x16x32_bf16 v[54:57], v[142:145], v[174:177], v[54:57]
	v_mfma_f32_16x16x32_bf16 v[58:61], v[134:137], v[166:169], v[58:61]
	v_mfma_f32_16x16x32_bf16 v[62:65], v[142:145], v[166:169], v[62:65]
	s_setprio 0
	s_add_i32 s69, s69, 2
	s_add_u32 s26, s26, 0x100
	s_addc_u32 s27, s27, 0
	s_cmp_gt_u32 s69, 41
	s_barrier
	s_cbranch_scc1 .LBB0_2065

.LBB0_2113:
	s_waitcnt lgkmcnt(0)
	s_barrier
	s_setprio 1
	s_waitcnt lgkmcnt(0)
	v_mfma_f32_16x16x32_bf16 v[48:51], v[152:155], v[184:187], v[48:51]
	v_mfma_f32_16x16x32_bf16 v[52:55], v[144:147], v[184:187], v[52:55]
	v_mfma_f32_16x16x32_bf16 v[32:35], v[152:155], v[176:179], v[32:35]
	v_mfma_f32_16x16x32_bf16 v[36:39], v[144:147], v[176:179], v[36:39]
	v_mfma_f32_16x16x32_bf16 v[16:19], v[152:155], v[168:171], v[16:19]
	v_mfma_f32_16x16x32_bf16 v[20:23], v[144:147], v[168:171], v[20:23]
	v_mfma_f32_16x16x32_bf16 v[12:15], v[152:155], v[160:163], v[12:15]
	v_mfma_f32_16x16x32_bf16 v[4:7], v[144:147], v[160:163], v[4:7]
	v_mfma_f32_16x16x32_bf16 v[48:51], v[156:159], v[188:191], v[48:51]
	v_mfma_f32_16x16x32_bf16 v[52:55], v[148:151], v[188:191], v[52:55]
	v_mfma_f32_16x16x32_bf16 v[32:35], v[156:159], v[180:183], v[32:35]
	v_mfma_f32_16x16x32_bf16 v[36:39], v[148:151], v[180:183], v[36:39]
	v_mfma_f32_16x16x32_bf16 v[16:19], v[156:159], v[172:175], v[16:19]
	v_mfma_f32_16x16x32_bf16 v[20:23], v[148:151], v[172:175], v[20:23]
	v_mfma_f32_16x16x32_bf16 v[12:15], v[156:159], v[164:167], v[12:15]
	v_mfma_f32_16x16x32_bf16 v[4:7], v[148:151], v[164:167], v[4:7]
	s_setprio 0
	s_setprio 1
	v_mfma_f32_16x16x32_bf16 v[56:59], v[136:139], v[184:187], v[56:59]
	v_mfma_f32_16x16x32_bf16 v[60:63], v[128:131], v[184:187], v[60:63]
	v_mfma_f32_16x16x32_bf16 v[40:43], v[136:139], v[176:179], v[40:43]
	v_mfma_f32_16x16x32_bf16 v[44:47], v[128:131], v[176:179], v[44:47]
	v_mfma_f32_16x16x32_bf16 v[24:27], v[136:139], v[168:171], v[24:27]
	v_mfma_f32_16x16x32_bf16 v[28:31], v[128:131], v[168:171], v[28:31]
	v_mfma_f32_16x16x32_bf16 v[8:11], v[136:139], v[160:163], v[8:11]
	v_mfma_f32_16x16x32_bf16 v[0:3], v[128:131], v[160:163], v[0:3]
	v_mfma_f32_16x16x32_bf16 v[56:59], v[140:143], v[188:191], v[56:59]
	v_mfma_f32_16x16x32_bf16 v[60:63], v[132:135], v[188:191], v[60:63]
	v_mfma_f32_16x16x32_bf16 v[40:43], v[140:143], v[180:183], v[40:43]
	v_mfma_f32_16x16x32_bf16 v[44:47], v[132:135], v[180:183], v[44:47]
	v_mfma_f32_16x16x32_bf16 v[24:27], v[140:143], v[172:175], v[24:27]
	v_mfma_f32_16x16x32_bf16 v[28:31], v[132:135], v[172:175], v[28:31]
	v_mfma_f32_16x16x32_bf16 v[8:11], v[140:143], v[164:167], v[8:11]
	v_mfma_f32_16x16x32_bf16 v[0:3], v[132:135], v[164:167], v[0:3]
	s_setprio 0
	s_add_i32 s75, s75, 2
	s_add_u32 s36, s36, 0x100
	s_addc_u32 s37, s37, 0
	s_cmp_gt_u32 s75, 41
	s_barrier
	s_cbranch_scc1 .LBB0_2126
